# gla_prep: next unit ticket prefetched mid-unit (atomic round trip off the critical path)
# baseline (speedup 1.0000x reference)
; DEVINL float bf2f(u16 h) { return __uint_as_float(((unsigned)h) << 16); }
; DEVINL int otid() { int t = threadIdx.x; asm volatile("" : "+v"(t)); return t; }
; DEVINL void gla_prep_unit(const Params& p, int unit) {
;   const int h = unit & 3, c = (unit >> 2) & 63, b = unit >> 8;
;   char* ws = p.ws;
;   const u16* cols = (const u16*)(ws + O_COLS);
;   const int tid = otid();
;   float* afab = (float*)dynsmem;
;   float* G = (float*)(dynsmem + 8192);
;   u16* KD = (u16*)(dynsmem + 8192 + 65536);
;   u16* VL = (u16*)dynsmem;
;   const long tok0 = (long)b * S_ + c * 64;
;   for (int i = tid; i < 64 * 32; i += 512) {
;     int r = i >> 5, cc = i & 31;
;     afab[i] = bf2f(cols[(tok0 + r) * NCP + C_AF + cc]);
;   }
;   __syncthreads();
;   if (tid < 256) {
;     const int dir = tid >> 7, kk = tid & 127;
;     const float* up = dir ? p.gla_a_up_b : p.gla_a_up_f;
;     const float bias = (dir ? p.gla_a_bias_b : p.gla_a_bias_f)[h * 128 + kk];
;     float u[16];
; #pragma unroll
;     for (int r = 0; r < 16; ++r) u[r] = up[r * 512 + h * 128 + kk];
;     float* Gc = G + dir * 64 * 128 + kk;
; DEVINL void phase2(const Params& p) {
;     ...
;   for (int u = bid; u < 512; u += nb) gla_prep_unit(p, u);
.LBB0_387:
	v_readlane_b32 s80, v255, 20
	v_readlane_b32 s81, v255, 21
	v_readlane_b32 s82, v255, 22
	v_readlane_b32 s83, v255, 23
	v_readlane_b32 s84, v255, 24
	v_readlane_b32 s85, v255, 25
	v_readlane_b32 s86, v255, 26
	v_readlane_b32 s87, v255, 27
	s_nop 4
	v_mov_b32_e32 v0, v189
	v_and_b32_e32 v1, 0x7f, v0
	v_lshlrev_b32_e32 v2, 4, v0
	v_lshrrev_b32_e32 v3, 6, v0
	s_nop 0
	v_readfirstlane_b32 s70, v3
	s_nop 3
	s_lshr_b32 s71, s70, 2
	s_bfe_u32 s6, s70, 0x10001
	v_lshrrev_b32_e32 v4, 3, v0
	v_mul_u32_u24_e32 v4, 0x5400, v4
	v_and_b32_e32 v5, 7, v0
	v_lshl_add_u32 v4, v5, 3, v4
	v_add_u32_e32 v4, 0x1800, v4
	v_lshrrev_b32_e32 v5, 4, v0
	v_mul_u32_u24_e32 v5, 0x5400, v5
	v_and_b32_e32 v6, 15, v0
	v_lshl_add_u32 v5, v6, 4, v5
	v_lshrrev_b32_e32 v6, 5, v0
	v_mul_u32_u24_e32 v6, 0x5400, v6
	v_and_b32_e32 v7, 31, v0
	v_lshl_add_u32 v6, v7, 4, v6
	v_lshlrev_b32_e32 v7, 2, v1
	v_and_b32_e32 v8, 0xff, v0
	v_lshrrev_b32_e32 v9, 8, v0
	v_lshlrev_b32_e32 v10, 1, v8
	v_lshl_add_u32 v10, v9, 14, v10
	v_add_u32_e32 v10, 0xa010, v10
	v_lshlrev_b32_e32 v11, 7, v8
	v_lshl_add_u32 v11, v9, 6, v11
	s_lshl_b32 s7, s71, 6
	s_lshl_b32 s8, s6, 12
	s_add_u32 s7, s7, s8
	s_add_u32 s7, s7, 16
	v_mov_b32_e32 v12, s7
	s_lshl_b32 s7, s6, 1
	s_add_u32 s7, s7, s71
	s_lshl_b32 s7, s7, 9
	s_add_u32 s7, s7, 106512
	v_add_u32_e32 v13, s7, v7
	s_xor_b32 s8, s6, 1
	s_lshl_b32 s8, s8, 1
	s_add_u32 s8, s8, s71
	s_lshl_b32 s8, s8, 9
	s_add_u32 s8, s8, 106512
	v_add_u32_e32 v14, s8, v7
	s_lshl_b32 s8, s71, 9
	s_add_u32 s8, s8, 108560
	v_add_u32_e32 v15, s8, v7
	s_lshl_b32 s8, s6, 13
	s_add_u32 s8, s8, 24592
	v_lshl_add_u32 v16, v1, 1, s8
	s_lshl_b32 s8, s71, 15
	s_lshl_b32 s9, s6, 14
	s_add_u32 s8, s8, s9
	s_add_u32 s8, s8, 40976
	v_add_u32_e32 v17, s8, v7
	v_lshlrev_b32_e32 v18, 7, v1
	s_lshl_b32 s8, s6, 6
	v_add_u32_e32 v18, s8, v18
	v_and_b32_e32 v19, 15, v0
	v_lshrrev_b32_e32 v20, 2, v19
	v_and_b32_e32 v21, 3, v19
	v_lshlrev_b32_e32 v20, 5, v20
	v_lshl_add_u32 v20, v21, 2, v20
	v_lshrrev_b32_e32 v21, 4, v0
	v_lshlrev_b32_e32 v22, 9, v21
	v_lshl_add_u32 v22, v20, 2, v22
	v_add_u32_e32 v22, 0xa010, v22
	v_lshlrev_b32_e32 v23, 8, v21
	v_lshl_add_u32 v23, v20, 1, v23
	v_add_u32_e32 v23, 0x2010, v23
	s_cmp_eq_u32 s71, 0
	s_cselect_b32 s36, s80, s84
	s_cselect_b32 s37, s81, s85
	s_cselect_b32 s38, s82, s86
	s_cselect_b32 s39, s83, s87
	s_xor_b32 s40, s71, s6
	s_cmp_lg_u32 s70, 0
	s_cbranch_scc1 .Lgl_nopf0
	s_mov_b64 exec, 1
	v_mov_b32_e32 v31, 1
	v_mov_b32_e32 v81, 0
	global_atomic_add v30, v81, v31, s[96:97] offset:4 sc0
	s_mov_b64 exec, -1
.Lgl_nopf0:
.Lgl_unit:
	s_cmp_lg_u32 s70, 0
	s_cbranch_scc1 .Lgl_nofetch
	s_mov_b64 exec, 1
	s_waitcnt vmcnt(0)
	v_mov_b32_e32 v28, 8
	ds_write_b32 v28, v30
	s_waitcnt lgkmcnt(0)
	s_mov_b64 exec, -1
.Lgl_nofetch:
	s_barrier
	v_mov_b32_e32 v28, 8
	ds_read_b32 v29, v28
	s_waitcnt lgkmcnt(0)
	v_readfirstlane_b32 s3, v29
	s_nop 3
	s_cmp_ge_u32 s3, 0x200
	s_cbranch_scc1 .Lgl_done
	s_and_b32 s41, s3, 3
	s_bfe_u32 s42, s3, 0x60002
	s_lshr_b32 s43, s3, 8
	s_lshl_b32 s44, s43, 12
	s_lshl_b32 s45, s42, 6
	s_add_u32 s44, s44, s45
	s_mul_i32 s44, s44, 0x5400
	s_add_u32 s46, s92, s44
	s_addc_u32 s47, s93, 0
	s_add_u32 s46, s46, 0x4c00000
	s_addc_u32 s47, s47, 0
	global_load_dwordx2 v[82:83], v4, s[46:47] nt
	s_lshl_b32 s48, s41, 8
	s_add_u32 s48, s46, s48
	s_addc_u32 s49, s47, 0
	global_load_dwordx4 v[84:87], v5, s[48:49] nt
	global_load_dwordx4 v[92:95], v5, s[48:49] offset:1024 nt
	s_add_u32 s50, s48, 0xa8000
	s_addc_u32 s51, s49, 0
	global_load_dwordx4 v[88:91], v5, s[50:51] nt
	global_load_dwordx4 v[96:99], v5, s[50:51] offset:1024 nt
	s_lshl_b32 s48, s41, 9
	s_add_u32 s48, s46, s48
	s_addc_u32 s49, s47, 0
	global_load_dwordx4 v[100:103], v6, s[48:49] offset:2048 nt
	s_add_u32 s48, s48, 0x54000
	s_addc_u32 s49, s49, 0
	global_load_dwordx4 v[104:107], v6, s[48:49] offset:2048 nt
	s_add_u32 s48, s48, 0x54000
	s_addc_u32 s49, s49, 0
	global_load_dwordx4 v[108:111], v6, s[48:49] offset:2048 nt
	s_add_u32 s48, s48, 0x54000
	s_addc_u32 s49, s49, 0
	global_load_dwordx4 v[112:115], v6, s[48:49] offset:2048 nt
	s_lshl_b32 s48, s41, 9
	v_add_u32_e32 v24, s48, v7
	global_load_dword v64, v24, s[36:37] offset:0
	global_load_dword v65, v24, s[36:37] offset:2048
	v_add_u32_e32 v24, 0x1000, v24
	global_load_dword v66, v24, s[36:37] offset:0
	global_load_dword v67, v24, s[36:37] offset:2048
	v_add_u32_e32 v24, 0x1000, v24
	global_load_dword v68, v24, s[36:37] offset:0
	global_load_dword v69, v24, s[36:37] offset:2048
	v_add_u32_e32 v24, 0x1000, v24
	global_load_dword v70, v24, s[36:37] offset:0
	global_load_dword v71, v24, s[36:37] offset:2048
	v_add_u32_e32 v24, 0x1000, v24
	global_load_dword v72, v24, s[36:37] offset:0
	global_load_dword v73, v24, s[36:37] offset:2048
	v_add_u32_e32 v24, 0x1000, v24
	global_load_dword v74, v24, s[36:37] offset:0
	global_load_dword v75, v24, s[36:37] offset:2048
	v_add_u32_e32 v24, 0x1000, v24
	global_load_dword v76, v24, s[36:37] offset:0
	global_load_dword v77, v24, s[36:37] offset:2048
	v_add_u32_e32 v24, 0x1000, v24
	global_load_dword v78, v24, s[36:37] offset:0
	global_load_dword v79, v24, s[36:37] offset:2048
	v_add_u32_e32 v25, s48, v7
	global_load_dword v80, v25, s[38:39]
	s_waitcnt vmcnt(25)
	v_lshlrev_b32_e32 v116, 16, v82
	v_and_b32_e32 v117, 0xffff0000, v82
	v_lshlrev_b32_e32 v118, 16, v83
	v_and_b32_e32 v119, 0xffff0000, v83
	ds_write_b128 v2, v[116:119] offset:16
	s_waitcnt vmcnt(21)
	ds_write_b128 v2, v[84:87] offset:8208
	ds_write_b128 v2, v[92:95] offset:24592
	ds_write_b128 v2, v[88:91] offset:16400
	ds_write_b128 v2, v[96:99] offset:32784
	s_waitcnt vmcnt(17)
	v_add_u32_e32 v26, 0x8000, v2
	ds_write_b128 v2, v[100:103] offset:40976
	ds_write_b128 v2, v[104:107] offset:49168
	ds_write_b128 v26, v[108:111] offset:24592
	ds_write_b128 v26, v[112:115] offset:32784
	s_waitcnt lgkmcnt(0)
	s_barrier
; DEVINL float logsig(float z) { return fminf(z, 0.f) - __logf(1.f + __expf(-fabsf(z))); }
; DEVINL int fragpos(int idx) { const int w = idx & 31; return (idx & ~31) + (((w & 15) >> 2) << 3) + (w & 3) + ((w >> 4) << 2); }
; DEVINL void gla_prep_unit(const Params& p, int unit) {
;     ...
;     for (int i = 0; i < 64; ++i) {
;       float z = bias;
; #pragma unroll
;       for (int r = 0; r < 16; ++r) z += afab[i * 32 + dir * 16 + r] * u[r];
;       Gc[i * 128] = logsig(z) * (1.f / 16.f);
;     ...
;   for (int idx = tid; idx < 64 * 256; idx += 512) {
;     int i = idx >> 8, vc = idx & 255;
;     VL[vc * 72 + fragpos(i)] = cols[(tok0 + i) * NCP + C_V + h * 256 + vc];
;   }
;   __syncthreads();
;   for (int pc = tid; pc < 4096; pc += 512) {
;     int row = pc >> 3, ch = pc & 7;
;     if (row < 256) {
;       int dir = row >> 7, kk = row & 127;
;       uint4 v = *(const uint4*)(KD + row * 72 + ch * 8);
;       long hb = ((long)(dir * 2 + b) * 4 + h);
;       *(uint4*)((u16*)(ws + O_KDT) + ((hb * 64 + c) * 128 + kk) * 64 + ch * 8) = v;
;     } else {
;       int vc = row - 256;
;       uint4 v = *(const uint4*)(VL + vc * 72 + ch * 8);
;       long hb = ((long)b * 4 + h);
;       *(uint4*)((u16*)(ws + O_VT) + ((hb * 64 + c) * 256 + vc) * 64 + ch * 8) = v;
	ds_read_u16 v192, v10 offset:0
	ds_read_u16 v193, v10 offset:512
	ds_read_u16 v194, v10 offset:1024
	ds_read_u16 v195, v10 offset:1536
	ds_read_u16 v196, v10 offset:2048
	ds_read_u16 v197, v10 offset:2560
	ds_read_u16 v198, v10 offset:3072
	ds_read_u16 v199, v10 offset:3584
	ds_read_u16 v200, v10 offset:4096
	ds_read_u16 v201, v10 offset:4608
	ds_read_u16 v202, v10 offset:5120
	ds_read_u16 v203, v10 offset:5632
	ds_read_u16 v204, v10 offset:6144
	ds_read_u16 v205, v10 offset:6656
	ds_read_u16 v206, v10 offset:7168
	ds_read_u16 v207, v10 offset:7680
	ds_read_u16 v208, v10 offset:8192
	ds_read_u16 v209, v10 offset:8704
	ds_read_u16 v210, v10 offset:9216
	ds_read_u16 v211, v10 offset:9728
	ds_read_u16 v212, v10 offset:10240
	ds_read_u16 v213, v10 offset:10752
	ds_read_u16 v214, v10 offset:11264
	ds_read_u16 v215, v10 offset:11776
	ds_read_u16 v216, v10 offset:12288
	ds_read_u16 v217, v10 offset:12800
	ds_read_u16 v218, v10 offset:13312
	ds_read_u16 v219, v10 offset:13824
	ds_read_u16 v220, v10 offset:14336
	ds_read_u16 v221, v10 offset:14848
	ds_read_u16 v222, v10 offset:15360
	ds_read_u16 v223, v10 offset:15872
	s_lshl_b32 s48, s43, 2
	s_add_u32 s48, s48, s41
	s_lshl_b32 s48, s48, 6
	s_add_u32 s48, s48, s42
	s_lshl_b32 s48, s48, 15
	s_add_u32 s48, s92, s48
	s_addc_u32 s49, s93, 0
	s_add_u32 s48, s48, 0x1a400000
	s_addc_u32 s49, s49, 0
	s_waitcnt lgkmcnt(0)
	v_lshl_or_b32 v144, v193, 16, v192
	v_lshl_or_b32 v145, v195, 16, v194
	v_lshl_or_b32 v146, v209, 16, v208
	v_lshl_or_b32 v147, v211, 16, v210
	v_lshl_or_b32 v148, v197, 16, v196
	v_lshl_or_b32 v149, v199, 16, v198
	v_lshl_or_b32 v150, v213, 16, v212
	v_lshl_or_b32 v151, v215, 16, v214
	v_lshl_or_b32 v152, v201, 16, v200
	v_lshl_or_b32 v153, v203, 16, v202
	v_lshl_or_b32 v154, v217, 16, v216
	v_lshl_or_b32 v155, v219, 16, v218
	v_lshl_or_b32 v156, v205, 16, v204
	v_lshl_or_b32 v157, v207, 16, v206
	v_lshl_or_b32 v158, v221, 16, v220
	v_lshl_or_b32 v159, v223, 16, v222
	global_store_dwordx4 v11, v[144:147], s[48:49] offset:0
	global_store_dwordx4 v11, v[148:151], s[48:49] offset:16
	global_store_dwordx4 v11, v[152:155], s[48:49] offset:32
	global_store_dwordx4 v11, v[156:159], s[48:49] offset:48
	s_waitcnt vmcnt(4)
	s_cmp_lg_u32 s70, 0
	s_cbranch_scc1 .Lgl_nopf
	s_mov_b64 exec, 1
	v_mov_b32_e32 v31, 1
	v_mov_b32_e32 v81, 0
	global_atomic_add v30, v81, v31, s[96:97] offset:4 sc0
	s_mov_b64 exec, -1
.Lgl_nopf:
	s_mov_b32 s52, 0xbfb8aa3b
	s_mov_b32 s53, 0x3f317217
	ds_read_b128 v[116:119], v12 offset:0
	ds_read_b128 v[120:123], v12 offset:16
	ds_read_b128 v[124:127], v12 offset:32
	ds_read_b128 v[128:131], v12 offset:48
	v_mov_b32_e32 v32, v80
	s_waitcnt lgkmcnt(3)
	v_fmac_f32_e32 v32, v116, v64
	v_fmac_f32_e32 v32, v117, v65
	v_fmac_f32_e32 v32, v118, v66
	v_fmac_f32_e32 v32, v119, v67
	s_waitcnt lgkmcnt(2)
	v_fmac_f32_e32 v32, v120, v68
	v_fmac_f32_e32 v32, v121, v69
	v_fmac_f32_e32 v32, v122, v70
	v_fmac_f32_e32 v32, v123, v71
	s_waitcnt lgkmcnt(1)
	v_fmac_f32_e32 v32, v124, v72
	v_fmac_f32_e32 v32, v125, v73
	v_fmac_f32_e32 v32, v126, v74
	v_fmac_f32_e32 v32, v127, v75
	s_waitcnt lgkmcnt(0)
	v_fmac_f32_e32 v32, v128, v76
	v_fmac_f32_e32 v32, v129, v77
	v_fmac_f32_e32 v32, v130, v78
	v_fmac_f32_e32 v32, v131, v79
	v_min_f32_e32 v132, 0, v32
	v_mul_f32_e64 v32, |v32|, s52
	v_exp_f32_e32 v32, v32
	s_nop 0
	v_add_f32_e32 v32, 1.0, v32
	v_log_f32_e32 v32, v32
	s_nop 0
	v_mul_f32_e32 v133, 0x3f317217, v32
	v_fma_f32 v133, v32, s53, -v133
	v_fmac_f32_e32 v133, 0x3377d1cf, v32
	v_fmac_f32_e32 v133, 0x3f317217, v32
	v_sub_f32_e32 v32, v132, v133
	v_mul_f32_e32 v32, 0x3d800000, v32
	ds_read_b128 v[116:119], v12 offset:128
	ds_read_b128 v[120:123], v12 offset:144
	ds_read_b128 v[124:127], v12 offset:160
	ds_read_b128 v[128:131], v12 offset:176
	v_mov_b32_e32 v33, v80
	s_waitcnt lgkmcnt(3)
	v_fmac_f32_e32 v33, v116, v64
	v_fmac_f32_e32 v33, v117, v65
	v_fmac_f32_e32 v33, v118, v66
	v_fmac_f32_e32 v33, v119, v67
	s_waitcnt lgkmcnt(2)
	v_fmac_f32_e32 v33, v120, v68
	v_fmac_f32_e32 v33, v121, v69
	v_fmac_f32_e32 v33, v122, v70
	v_fmac_f32_e32 v33, v123, v71
	s_waitcnt lgkmcnt(1)
	v_fmac_f32_e32 v33, v124, v72
	v_fmac_f32_e32 v33, v125, v73
	v_fmac_f32_e32 v33, v126, v74
	v_fmac_f32_e32 v33, v127, v75
	s_waitcnt lgkmcnt(0)
	v_fmac_f32_e32 v33, v128, v76
	v_fmac_f32_e32 v33, v129, v77
	v_fmac_f32_e32 v33, v130, v78
	v_fmac_f32_e32 v33, v131, v79
	v_min_f32_e32 v132, 0, v33
	v_mul_f32_e64 v33, |v33|, s52
	v_exp_f32_e32 v33, v33
	s_nop 0
	v_add_f32_e32 v33, 1.0, v33
	v_log_f32_e32 v33, v33
	s_nop 0
	v_mul_f32_e32 v133, 0x3f317217, v33
	v_fma_f32 v133, v33, s53, -v133
	v_fmac_f32_e32 v133, 0x3377d1cf, v33
	v_fmac_f32_e32 v133, 0x3f317217, v33
	v_sub_f32_e32 v33, v132, v133
	v_mul_f32_e32 v33, 0x3d800000, v33
	ds_read_b128 v[116:119], v12 offset:256
	ds_read_b128 v[120:123], v12 offset:272
	ds_read_b128 v[124:127], v12 offset:288
	ds_read_b128 v[128:131], v12 offset:304
	v_mov_b32_e32 v34, v80
	s_waitcnt lgkmcnt(3)
	v_fmac_f32_e32 v34, v116, v64
	v_fmac_f32_e32 v34, v117, v65
	v_fmac_f32_e32 v34, v118, v66
	v_fmac_f32_e32 v34, v119, v67
	s_waitcnt lgkmcnt(2)
	v_fmac_f32_e32 v34, v120, v68
	v_fmac_f32_e32 v34, v121, v69
	v_fmac_f32_e32 v34, v122, v70
	v_fmac_f32_e32 v34, v123, v71
	s_waitcnt lgkmcnt(1)
	v_fmac_f32_e32 v34, v124, v72
	v_fmac_f32_e32 v34, v125, v73
	v_fmac_f32_e32 v34, v126, v74
	v_fmac_f32_e32 v34, v127, v75
	s_waitcnt lgkmcnt(0)
; DEVINL float logsig(float z) { return fminf(z, 0.f) - __logf(1.f + __expf(-fabsf(z))); }
; DEVINL void gla_prep_unit(const Params& p, int unit) {
;     ...
;     for (int i = 0; i < 64; ++i) {
;       float z = bias;
; #pragma unroll
;       for (int r = 0; r < 16; ++r) z += afab[i * 32 + dir * 16 + r] * u[r];
;       Gc[i * 128] = logsig(z) * (1.f / 16.f);
	v_fmac_f32_e32 v34, v128, v76
	v_fmac_f32_e32 v34, v129, v77
	v_fmac_f32_e32 v34, v130, v78
	v_fmac_f32_e32 v34, v131, v79
	v_min_f32_e32 v132, 0, v34
	v_mul_f32_e64 v34, |v34|, s52
	v_exp_f32_e32 v34, v34
	s_nop 0
	v_add_f32_e32 v34, 1.0, v34
	v_log_f32_e32 v34, v34
	s_nop 0
	v_mul_f32_e32 v133, 0x3f317217, v34
	v_fma_f32 v133, v34, s53, -v133
	v_fmac_f32_e32 v133, 0x3377d1cf, v34
	v_fmac_f32_e32 v133, 0x3f317217, v34
	v_sub_f32_e32 v34, v132, v133
	v_mul_f32_e32 v34, 0x3d800000, v34
	ds_read_b128 v[116:119], v12 offset:384
	ds_read_b128 v[120:123], v12 offset:400
	ds_read_b128 v[124:127], v12 offset:416
	ds_read_b128 v[128:131], v12 offset:432
	v_mov_b32_e32 v35, v80
	s_waitcnt lgkmcnt(3)
	v_fmac_f32_e32 v35, v116, v64
	v_fmac_f32_e32 v35, v117, v65
	v_fmac_f32_e32 v35, v118, v66
	v_fmac_f32_e32 v35, v119, v67
	s_waitcnt lgkmcnt(2)
	v_fmac_f32_e32 v35, v120, v68
	v_fmac_f32_e32 v35, v121, v69
	v_fmac_f32_e32 v35, v122, v70
	v_fmac_f32_e32 v35, v123, v71
	s_waitcnt lgkmcnt(1)
	v_fmac_f32_e32 v35, v124, v72
	v_fmac_f32_e32 v35, v125, v73
	v_fmac_f32_e32 v35, v126, v74
	v_fmac_f32_e32 v35, v127, v75
	s_waitcnt lgkmcnt(0)
	v_fmac_f32_e32 v35, v128, v76
	v_fmac_f32_e32 v35, v129, v77
	v_fmac_f32_e32 v35, v130, v78
	v_fmac_f32_e32 v35, v131, v79
	v_min_f32_e32 v132, 0, v35
	v_mul_f32_e64 v35, |v35|, s52
	v_exp_f32_e32 v35, v35
	s_nop 0
	v_add_f32_e32 v35, 1.0, v35
	v_log_f32_e32 v35, v35
	s_nop 0
	v_mul_f32_e32 v133, 0x3f317217, v35
	v_fma_f32 v133, v35, s53, -v133
	v_fmac_f32_e32 v133, 0x3377d1cf, v35
	v_fmac_f32_e32 v133, 0x3f317217, v35
	v_sub_f32_e32 v35, v132, v133
	v_mul_f32_e32 v35, 0x3d800000, v35
	ds_read_b128 v[116:119], v12 offset:512
	ds_read_b128 v[120:123], v12 offset:528
	ds_read_b128 v[124:127], v12 offset:544
	ds_read_b128 v[128:131], v12 offset:560
	v_mov_b32_e32 v36, v80
	s_waitcnt lgkmcnt(3)
	v_fmac_f32_e32 v36, v116, v64
	v_fmac_f32_e32 v36, v117, v65
	v_fmac_f32_e32 v36, v118, v66
	v_fmac_f32_e32 v36, v119, v67
	s_waitcnt lgkmcnt(2)
	v_fmac_f32_e32 v36, v120, v68
	v_fmac_f32_e32 v36, v121, v69
	v_fmac_f32_e32 v36, v122, v70
	v_fmac_f32_e32 v36, v123, v71
	s_waitcnt lgkmcnt(1)
	v_fmac_f32_e32 v36, v124, v72
	v_fmac_f32_e32 v36, v125, v73
	v_fmac_f32_e32 v36, v126, v74
	v_fmac_f32_e32 v36, v127, v75
	s_waitcnt lgkmcnt(0)
	v_fmac_f32_e32 v36, v128, v76
	v_fmac_f32_e32 v36, v129, v77
	v_fmac_f32_e32 v36, v130, v78
	v_fmac_f32_e32 v36, v131, v79
	v_min_f32_e32 v132, 0, v36
	v_mul_f32_e64 v36, |v36|, s52
	v_exp_f32_e32 v36, v36
	s_nop 0
	v_add_f32_e32 v36, 1.0, v36
	v_log_f32_e32 v36, v36
	s_nop 0
	v_mul_f32_e32 v133, 0x3f317217, v36
	v_fma_f32 v133, v36, s53, -v133
	v_fmac_f32_e32 v133, 0x3377d1cf, v36
	v_fmac_f32_e32 v133, 0x3f317217, v36
	v_sub_f32_e32 v36, v132, v133
	v_mul_f32_e32 v36, 0x3d800000, v36
	ds_read_b128 v[116:119], v12 offset:640
	ds_read_b128 v[120:123], v12 offset:656
	ds_read_b128 v[124:127], v12 offset:672
	ds_read_b128 v[128:131], v12 offset:688
	v_mov_b32_e32 v37, v80
	s_waitcnt lgkmcnt(3)
	v_fmac_f32_e32 v37, v116, v64
	v_fmac_f32_e32 v37, v117, v65
	v_fmac_f32_e32 v37, v118, v66
	v_fmac_f32_e32 v37, v119, v67
	s_waitcnt lgkmcnt(2)
	v_fmac_f32_e32 v37, v120, v68
	v_fmac_f32_e32 v37, v121, v69
	v_fmac_f32_e32 v37, v122, v70
	v_fmac_f32_e32 v37, v123, v71
	s_waitcnt lgkmcnt(1)
	v_fmac_f32_e32 v37, v124, v72
	v_fmac_f32_e32 v37, v125, v73
	v_fmac_f32_e32 v37, v126, v74
	v_fmac_f32_e32 v37, v127, v75
	s_waitcnt lgkmcnt(0)
	v_fmac_f32_e32 v37, v128, v76
	v_fmac_f32_e32 v37, v129, v77
	v_fmac_f32_e32 v37, v130, v78
	v_fmac_f32_e32 v37, v131, v79
	v_min_f32_e32 v132, 0, v37
	v_mul_f32_e64 v37, |v37|, s52
	v_exp_f32_e32 v37, v37
	s_nop 0
	v_add_f32_e32 v37, 1.0, v37
	v_log_f32_e32 v37, v37
	s_nop 0
	v_mul_f32_e32 v133, 0x3f317217, v37
	v_fma_f32 v133, v37, s53, -v133
	v_fmac_f32_e32 v133, 0x3377d1cf, v37
	v_fmac_f32_e32 v133, 0x3f317217, v37
	v_sub_f32_e32 v37, v132, v133
	v_mul_f32_e32 v37, 0x3d800000, v37
	ds_read_b128 v[116:119], v12 offset:768
	ds_read_b128 v[120:123], v12 offset:784
	ds_read_b128 v[124:127], v12 offset:800
	ds_read_b128 v[128:131], v12 offset:816
	v_mov_b32_e32 v38, v80
	s_waitcnt lgkmcnt(3)
	v_fmac_f32_e32 v38, v116, v64
	v_fmac_f32_e32 v38, v117, v65
	v_fmac_f32_e32 v38, v118, v66
	v_fmac_f32_e32 v38, v119, v67
	s_waitcnt lgkmcnt(2)
	v_fmac_f32_e32 v38, v120, v68
	v_fmac_f32_e32 v38, v121, v69
	v_fmac_f32_e32 v38, v122, v70
	v_fmac_f32_e32 v38, v123, v71
	s_waitcnt lgkmcnt(1)
	v_fmac_f32_e32 v38, v124, v72
	v_fmac_f32_e32 v38, v125, v73
	v_fmac_f32_e32 v38, v126, v74
	v_fmac_f32_e32 v38, v127, v75
	s_waitcnt lgkmcnt(0)
	v_fmac_f32_e32 v38, v128, v76
	v_fmac_f32_e32 v38, v129, v77
	v_fmac_f32_e32 v38, v130, v78
	v_fmac_f32_e32 v38, v131, v79
	v_min_f32_e32 v132, 0, v38
	v_mul_f32_e64 v38, |v38|, s52
	v_exp_f32_e32 v38, v38
	s_nop 0
	v_add_f32_e32 v38, 1.0, v38
	v_log_f32_e32 v38, v38
	s_nop 0
	v_mul_f32_e32 v133, 0x3f317217, v38
	v_fma_f32 v133, v38, s53, -v133
	v_fmac_f32_e32 v133, 0x3377d1cf, v38
	v_fmac_f32_e32 v133, 0x3f317217, v38
	v_sub_f32_e32 v38, v132, v133
	v_mul_f32_e32 v38, 0x3d800000, v38
	ds_read_b128 v[116:119], v12 offset:896
	ds_read_b128 v[120:123], v12 offset:912
	ds_read_b128 v[124:127], v12 offset:928
	ds_read_b128 v[128:131], v12 offset:944
	v_mov_b32_e32 v39, v80
	s_waitcnt lgkmcnt(3)
	v_fmac_f32_e32 v39, v116, v64
	v_fmac_f32_e32 v39, v117, v65
	v_fmac_f32_e32 v39, v118, v66
	v_fmac_f32_e32 v39, v119, v67
	s_waitcnt lgkmcnt(2)
	v_fmac_f32_e32 v39, v120, v68
	v_fmac_f32_e32 v39, v121, v69
	v_fmac_f32_e32 v39, v122, v70
	v_fmac_f32_e32 v39, v123, v71
	s_waitcnt lgkmcnt(1)
	v_fmac_f32_e32 v39, v124, v72
	v_fmac_f32_e32 v39, v125, v73
	v_fmac_f32_e32 v39, v126, v74
	v_fmac_f32_e32 v39, v127, v75
	s_waitcnt lgkmcnt(0)
; DEVINL float logsig(float z) { return fminf(z, 0.f) - __logf(1.f + __expf(-fabsf(z))); }
; DEVINL void gla_prep_unit(const Params& p, int unit) {
;     ...
;     for (int i = 0; i < 64; ++i) {
;       float z = bias;
; #pragma unroll
;       for (int r = 0; r < 16; ++r) z += afab[i * 32 + dir * 16 + r] * u[r];
;       Gc[i * 128] = logsig(z) * (1.f / 16.f);
	v_fmac_f32_e32 v39, v128, v76
	v_fmac_f32_e32 v39, v129, v77
	v_fmac_f32_e32 v39, v130, v78
	v_fmac_f32_e32 v39, v131, v79
	v_min_f32_e32 v132, 0, v39
	v_mul_f32_e64 v39, |v39|, s52
	v_exp_f32_e32 v39, v39
	s_nop 0
	v_add_f32_e32 v39, 1.0, v39
	v_log_f32_e32 v39, v39
	s_nop 0
	v_mul_f32_e32 v133, 0x3f317217, v39
	v_fma_f32 v133, v39, s53, -v133
	v_fmac_f32_e32 v133, 0x3377d1cf, v39
	v_fmac_f32_e32 v133, 0x3f317217, v39
	v_sub_f32_e32 v39, v132, v133
	v_mul_f32_e32 v39, 0x3d800000, v39
	ds_read_b128 v[116:119], v12 offset:1024
	ds_read_b128 v[120:123], v12 offset:1040
	ds_read_b128 v[124:127], v12 offset:1056
	ds_read_b128 v[128:131], v12 offset:1072
	v_mov_b32_e32 v40, v80
	s_waitcnt lgkmcnt(3)
	v_fmac_f32_e32 v40, v116, v64
	v_fmac_f32_e32 v40, v117, v65
	v_fmac_f32_e32 v40, v118, v66
	v_fmac_f32_e32 v40, v119, v67
	s_waitcnt lgkmcnt(2)
	v_fmac_f32_e32 v40, v120, v68
	v_fmac_f32_e32 v40, v121, v69
	v_fmac_f32_e32 v40, v122, v70
	v_fmac_f32_e32 v40, v123, v71
	s_waitcnt lgkmcnt(1)
	v_fmac_f32_e32 v40, v124, v72
	v_fmac_f32_e32 v40, v125, v73
	v_fmac_f32_e32 v40, v126, v74
	v_fmac_f32_e32 v40, v127, v75
	s_waitcnt lgkmcnt(0)
	v_fmac_f32_e32 v40, v128, v76
	v_fmac_f32_e32 v40, v129, v77
	v_fmac_f32_e32 v40, v130, v78
	v_fmac_f32_e32 v40, v131, v79
	v_min_f32_e32 v132, 0, v40
	v_mul_f32_e64 v40, |v40|, s52
	v_exp_f32_e32 v40, v40
	s_nop 0
	v_add_f32_e32 v40, 1.0, v40
	v_log_f32_e32 v40, v40
	s_nop 0
	v_mul_f32_e32 v133, 0x3f317217, v40
	v_fma_f32 v133, v40, s53, -v133
	v_fmac_f32_e32 v133, 0x3377d1cf, v40
	v_fmac_f32_e32 v133, 0x3f317217, v40
	v_sub_f32_e32 v40, v132, v133
	v_mul_f32_e32 v40, 0x3d800000, v40
	ds_read_b128 v[116:119], v12 offset:1152
	ds_read_b128 v[120:123], v12 offset:1168
	ds_read_b128 v[124:127], v12 offset:1184
	ds_read_b128 v[128:131], v12 offset:1200
	v_mov_b32_e32 v41, v80
	s_waitcnt lgkmcnt(3)
	v_fmac_f32_e32 v41, v116, v64
	v_fmac_f32_e32 v41, v117, v65
	v_fmac_f32_e32 v41, v118, v66
	v_fmac_f32_e32 v41, v119, v67
	s_waitcnt lgkmcnt(2)
	v_fmac_f32_e32 v41, v120, v68
	v_fmac_f32_e32 v41, v121, v69
	v_fmac_f32_e32 v41, v122, v70
	v_fmac_f32_e32 v41, v123, v71
	s_waitcnt lgkmcnt(1)
	v_fmac_f32_e32 v41, v124, v72
	v_fmac_f32_e32 v41, v125, v73
	v_fmac_f32_e32 v41, v126, v74
	v_fmac_f32_e32 v41, v127, v75
	s_waitcnt lgkmcnt(0)
	v_fmac_f32_e32 v41, v128, v76
	v_fmac_f32_e32 v41, v129, v77
	v_fmac_f32_e32 v41, v130, v78
	v_fmac_f32_e32 v41, v131, v79
	v_min_f32_e32 v132, 0, v41
	v_mul_f32_e64 v41, |v41|, s52
	v_exp_f32_e32 v41, v41
	s_nop 0
	v_add_f32_e32 v41, 1.0, v41
	v_log_f32_e32 v41, v41
	s_nop 0
	v_mul_f32_e32 v133, 0x3f317217, v41
	v_fma_f32 v133, v41, s53, -v133
	v_fmac_f32_e32 v133, 0x3377d1cf, v41
	v_fmac_f32_e32 v133, 0x3f317217, v41
	v_sub_f32_e32 v41, v132, v133
	v_mul_f32_e32 v41, 0x3d800000, v41
	ds_read_b128 v[116:119], v12 offset:1280
	ds_read_b128 v[120:123], v12 offset:1296
	ds_read_b128 v[124:127], v12 offset:1312
	ds_read_b128 v[128:131], v12 offset:1328
	v_mov_b32_e32 v42, v80
	s_waitcnt lgkmcnt(3)
	v_fmac_f32_e32 v42, v116, v64
	v_fmac_f32_e32 v42, v117, v65
	v_fmac_f32_e32 v42, v118, v66
	v_fmac_f32_e32 v42, v119, v67
	s_waitcnt lgkmcnt(2)
	v_fmac_f32_e32 v42, v120, v68
	v_fmac_f32_e32 v42, v121, v69
	v_fmac_f32_e32 v42, v122, v70
	v_fmac_f32_e32 v42, v123, v71
	s_waitcnt lgkmcnt(1)
	v_fmac_f32_e32 v42, v124, v72
	v_fmac_f32_e32 v42, v125, v73
	v_fmac_f32_e32 v42, v126, v74
	v_fmac_f32_e32 v42, v127, v75
	s_waitcnt lgkmcnt(0)
	v_fmac_f32_e32 v42, v128, v76
	v_fmac_f32_e32 v42, v129, v77
	v_fmac_f32_e32 v42, v130, v78
	v_fmac_f32_e32 v42, v131, v79
	v_min_f32_e32 v132, 0, v42
	v_mul_f32_e64 v42, |v42|, s52
	v_exp_f32_e32 v42, v42
	s_nop 0
	v_add_f32_e32 v42, 1.0, v42
	v_log_f32_e32 v42, v42
	s_nop 0
	v_mul_f32_e32 v133, 0x3f317217, v42
	v_fma_f32 v133, v42, s53, -v133
	v_fmac_f32_e32 v133, 0x3377d1cf, v42
	v_fmac_f32_e32 v133, 0x3f317217, v42
	v_sub_f32_e32 v42, v132, v133
	v_mul_f32_e32 v42, 0x3d800000, v42
	ds_read_b128 v[116:119], v12 offset:1408
	ds_read_b128 v[120:123], v12 offset:1424
	ds_read_b128 v[124:127], v12 offset:1440
	ds_read_b128 v[128:131], v12 offset:1456
	v_mov_b32_e32 v43, v80
	s_waitcnt lgkmcnt(3)
	v_fmac_f32_e32 v43, v116, v64
	v_fmac_f32_e32 v43, v117, v65
	v_fmac_f32_e32 v43, v118, v66
	v_fmac_f32_e32 v43, v119, v67
	s_waitcnt lgkmcnt(2)
	v_fmac_f32_e32 v43, v120, v68
	v_fmac_f32_e32 v43, v121, v69
	v_fmac_f32_e32 v43, v122, v70
	v_fmac_f32_e32 v43, v123, v71
	s_waitcnt lgkmcnt(1)
	v_fmac_f32_e32 v43, v124, v72
	v_fmac_f32_e32 v43, v125, v73
	v_fmac_f32_e32 v43, v126, v74
	v_fmac_f32_e32 v43, v127, v75
	s_waitcnt lgkmcnt(0)
	v_fmac_f32_e32 v43, v128, v76
	v_fmac_f32_e32 v43, v129, v77
	v_fmac_f32_e32 v43, v130, v78
	v_fmac_f32_e32 v43, v131, v79
	v_min_f32_e32 v132, 0, v43
	v_mul_f32_e64 v43, |v43|, s52
	v_exp_f32_e32 v43, v43
	s_nop 0
	v_add_f32_e32 v43, 1.0, v43
	v_log_f32_e32 v43, v43
	s_nop 0
	v_mul_f32_e32 v133, 0x3f317217, v43
	v_fma_f32 v133, v43, s53, -v133
	v_fmac_f32_e32 v133, 0x3377d1cf, v43
	v_fmac_f32_e32 v133, 0x3f317217, v43
	v_sub_f32_e32 v43, v132, v133
	v_mul_f32_e32 v43, 0x3d800000, v43
	ds_read_b128 v[116:119], v12 offset:1536
	ds_read_b128 v[120:123], v12 offset:1552
	ds_read_b128 v[124:127], v12 offset:1568
	ds_read_b128 v[128:131], v12 offset:1584
	v_mov_b32_e32 v44, v80
	s_waitcnt lgkmcnt(3)
	v_fmac_f32_e32 v44, v116, v64
	v_fmac_f32_e32 v44, v117, v65
	v_fmac_f32_e32 v44, v118, v66
	v_fmac_f32_e32 v44, v119, v67
	s_waitcnt lgkmcnt(2)
	v_fmac_f32_e32 v44, v120, v68
	v_fmac_f32_e32 v44, v121, v69
	v_fmac_f32_e32 v44, v122, v70
	v_fmac_f32_e32 v44, v123, v71
	s_waitcnt lgkmcnt(1)
; DEVINL float logsig(float z) { return fminf(z, 0.f) - __logf(1.f + __expf(-fabsf(z))); }
; DEVINL void gla_prep_unit(const Params& p, int unit) {
;     ...
;     for (int i = 0; i < 64; ++i) {
;       float z = bias;
; #pragma unroll
;       for (int r = 0; r < 16; ++r) z += afab[i * 32 + dir * 16 + r] * u[r];
;       Gc[i * 128] = logsig(z) * (1.f / 16.f);
	v_fmac_f32_e32 v44, v124, v72
	v_fmac_f32_e32 v44, v125, v73
	v_fmac_f32_e32 v44, v126, v74
	v_fmac_f32_e32 v44, v127, v75
	s_waitcnt lgkmcnt(0)
	v_fmac_f32_e32 v44, v128, v76
	v_fmac_f32_e32 v44, v129, v77
	v_fmac_f32_e32 v44, v130, v78
	v_fmac_f32_e32 v44, v131, v79
	v_min_f32_e32 v132, 0, v44
	v_mul_f32_e64 v44, |v44|, s52
	v_exp_f32_e32 v44, v44
	s_nop 0
	v_add_f32_e32 v44, 1.0, v44
	v_log_f32_e32 v44, v44
	s_nop 0
	v_mul_f32_e32 v133, 0x3f317217, v44
	v_fma_f32 v133, v44, s53, -v133
	v_fmac_f32_e32 v133, 0x3377d1cf, v44
	v_fmac_f32_e32 v133, 0x3f317217, v44
	v_sub_f32_e32 v44, v132, v133
	v_mul_f32_e32 v44, 0x3d800000, v44
	ds_read_b128 v[116:119], v12 offset:1664
	ds_read_b128 v[120:123], v12 offset:1680
	ds_read_b128 v[124:127], v12 offset:1696
	ds_read_b128 v[128:131], v12 offset:1712
	v_mov_b32_e32 v45, v80
	s_waitcnt lgkmcnt(3)
	v_fmac_f32_e32 v45, v116, v64
	v_fmac_f32_e32 v45, v117, v65
	v_fmac_f32_e32 v45, v118, v66
	v_fmac_f32_e32 v45, v119, v67
	s_waitcnt lgkmcnt(2)
	v_fmac_f32_e32 v45, v120, v68
	v_fmac_f32_e32 v45, v121, v69
	v_fmac_f32_e32 v45, v122, v70
	v_fmac_f32_e32 v45, v123, v71
	s_waitcnt lgkmcnt(1)
	v_fmac_f32_e32 v45, v124, v72
	v_fmac_f32_e32 v45, v125, v73
	v_fmac_f32_e32 v45, v126, v74
	v_fmac_f32_e32 v45, v127, v75
	s_waitcnt lgkmcnt(0)
	v_fmac_f32_e32 v45, v128, v76
	v_fmac_f32_e32 v45, v129, v77
	v_fmac_f32_e32 v45, v130, v78
	v_fmac_f32_e32 v45, v131, v79
	v_min_f32_e32 v132, 0, v45
	v_mul_f32_e64 v45, |v45|, s52
	v_exp_f32_e32 v45, v45
	s_nop 0
	v_add_f32_e32 v45, 1.0, v45
	v_log_f32_e32 v45, v45
	s_nop 0
	v_mul_f32_e32 v133, 0x3f317217, v45
	v_fma_f32 v133, v45, s53, -v133
	v_fmac_f32_e32 v133, 0x3377d1cf, v45
	v_fmac_f32_e32 v133, 0x3f317217, v45
	v_sub_f32_e32 v45, v132, v133
	v_mul_f32_e32 v45, 0x3d800000, v45
	ds_read_b128 v[116:119], v12 offset:1792
	ds_read_b128 v[120:123], v12 offset:1808
	ds_read_b128 v[124:127], v12 offset:1824
	ds_read_b128 v[128:131], v12 offset:1840
	v_mov_b32_e32 v46, v80
	s_waitcnt lgkmcnt(3)
	v_fmac_f32_e32 v46, v116, v64
	v_fmac_f32_e32 v46, v117, v65
	v_fmac_f32_e32 v46, v118, v66
	v_fmac_f32_e32 v46, v119, v67
	s_waitcnt lgkmcnt(2)
	v_fmac_f32_e32 v46, v120, v68
	v_fmac_f32_e32 v46, v121, v69
	v_fmac_f32_e32 v46, v122, v70
	v_fmac_f32_e32 v46, v123, v71
	s_waitcnt lgkmcnt(1)
	v_fmac_f32_e32 v46, v124, v72
	v_fmac_f32_e32 v46, v125, v73
	v_fmac_f32_e32 v46, v126, v74
	v_fmac_f32_e32 v46, v127, v75
	s_waitcnt lgkmcnt(0)
	v_fmac_f32_e32 v46, v128, v76
	v_fmac_f32_e32 v46, v129, v77
	v_fmac_f32_e32 v46, v130, v78
	v_fmac_f32_e32 v46, v131, v79
	v_min_f32_e32 v132, 0, v46
	v_mul_f32_e64 v46, |v46|, s52
	v_exp_f32_e32 v46, v46
	s_nop 0
	v_add_f32_e32 v46, 1.0, v46
	v_log_f32_e32 v46, v46
	s_nop 0
	v_mul_f32_e32 v133, 0x3f317217, v46
	v_fma_f32 v133, v46, s53, -v133
	v_fmac_f32_e32 v133, 0x3377d1cf, v46
	v_fmac_f32_e32 v133, 0x3f317217, v46
	v_sub_f32_e32 v46, v132, v133
	v_mul_f32_e32 v46, 0x3d800000, v46
	ds_read_b128 v[116:119], v12 offset:1920
	ds_read_b128 v[120:123], v12 offset:1936
	ds_read_b128 v[124:127], v12 offset:1952
	ds_read_b128 v[128:131], v12 offset:1968
	v_mov_b32_e32 v47, v80
	s_waitcnt lgkmcnt(3)
	v_fmac_f32_e32 v47, v116, v64
	v_fmac_f32_e32 v47, v117, v65
	v_fmac_f32_e32 v47, v118, v66
	v_fmac_f32_e32 v47, v119, v67
	s_waitcnt lgkmcnt(2)
	v_fmac_f32_e32 v47, v120, v68
	v_fmac_f32_e32 v47, v121, v69
	v_fmac_f32_e32 v47, v122, v70
	v_fmac_f32_e32 v47, v123, v71
	s_waitcnt lgkmcnt(1)
	v_fmac_f32_e32 v47, v124, v72
	v_fmac_f32_e32 v47, v125, v73
	v_fmac_f32_e32 v47, v126, v74
	v_fmac_f32_e32 v47, v127, v75
	s_waitcnt lgkmcnt(0)
	v_fmac_f32_e32 v47, v128, v76
	v_fmac_f32_e32 v47, v129, v77
	v_fmac_f32_e32 v47, v130, v78
	v_fmac_f32_e32 v47, v131, v79
	v_min_f32_e32 v132, 0, v47
	v_mul_f32_e64 v47, |v47|, s52
	v_exp_f32_e32 v47, v47
	s_nop 0
	v_add_f32_e32 v47, 1.0, v47
	v_log_f32_e32 v47, v47
	s_nop 0
	v_mul_f32_e32 v133, 0x3f317217, v47
	v_fma_f32 v133, v47, s53, -v133
	v_fmac_f32_e32 v133, 0x3377d1cf, v47
	v_fmac_f32_e32 v133, 0x3f317217, v47
	v_sub_f32_e32 v47, v132, v133
	v_mul_f32_e32 v47, 0x3d800000, v47
	ds_read_b128 v[116:119], v12 offset:2048
	ds_read_b128 v[120:123], v12 offset:2064
	ds_read_b128 v[124:127], v12 offset:2080
	ds_read_b128 v[128:131], v12 offset:2096
	v_mov_b32_e32 v48, v80
	s_waitcnt lgkmcnt(3)
	v_fmac_f32_e32 v48, v116, v64
	v_fmac_f32_e32 v48, v117, v65
	v_fmac_f32_e32 v48, v118, v66
	v_fmac_f32_e32 v48, v119, v67
	s_waitcnt lgkmcnt(2)
	v_fmac_f32_e32 v48, v120, v68
	v_fmac_f32_e32 v48, v121, v69
	v_fmac_f32_e32 v48, v122, v70
	v_fmac_f32_e32 v48, v123, v71
	s_waitcnt lgkmcnt(1)
	v_fmac_f32_e32 v48, v124, v72
	v_fmac_f32_e32 v48, v125, v73
	v_fmac_f32_e32 v48, v126, v74
	v_fmac_f32_e32 v48, v127, v75
	s_waitcnt lgkmcnt(0)
	v_fmac_f32_e32 v48, v128, v76
	v_fmac_f32_e32 v48, v129, v77
	v_fmac_f32_e32 v48, v130, v78
	v_fmac_f32_e32 v48, v131, v79
	v_min_f32_e32 v132, 0, v48
	v_mul_f32_e64 v48, |v48|, s52
	v_exp_f32_e32 v48, v48
	s_nop 0
	v_add_f32_e32 v48, 1.0, v48
	v_log_f32_e32 v48, v48
	s_nop 0
	v_mul_f32_e32 v133, 0x3f317217, v48
	v_fma_f32 v133, v48, s53, -v133
	v_fmac_f32_e32 v133, 0x3377d1cf, v48
	v_fmac_f32_e32 v133, 0x3f317217, v48
	v_sub_f32_e32 v48, v132, v133
	v_mul_f32_e32 v48, 0x3d800000, v48
	ds_read_b128 v[116:119], v12 offset:2176
	ds_read_b128 v[120:123], v12 offset:2192
	ds_read_b128 v[124:127], v12 offset:2208
	ds_read_b128 v[128:131], v12 offset:2224
	v_mov_b32_e32 v49, v80
	s_waitcnt lgkmcnt(3)
	v_fmac_f32_e32 v49, v116, v64
	v_fmac_f32_e32 v49, v117, v65
	v_fmac_f32_e32 v49, v118, v66
	v_fmac_f32_e32 v49, v119, v67
	s_waitcnt lgkmcnt(2)
; DEVINL float logsig(float z) { return fminf(z, 0.f) - __logf(1.f + __expf(-fabsf(z))); }
; DEVINL void gla_prep_unit(const Params& p, int unit) {
;     ...
;     for (int i = 0; i < 64; ++i) {
;       float z = bias;
; #pragma unroll
;       for (int r = 0; r < 16; ++r) z += afab[i * 32 + dir * 16 + r] * u[r];
;       Gc[i * 128] = logsig(z) * (1.f / 16.f);
	v_fmac_f32_e32 v49, v120, v68
	v_fmac_f32_e32 v49, v121, v69
	v_fmac_f32_e32 v49, v122, v70
	v_fmac_f32_e32 v49, v123, v71
	s_waitcnt lgkmcnt(1)
	v_fmac_f32_e32 v49, v124, v72
	v_fmac_f32_e32 v49, v125, v73
	v_fmac_f32_e32 v49, v126, v74
	v_fmac_f32_e32 v49, v127, v75
	s_waitcnt lgkmcnt(0)
	v_fmac_f32_e32 v49, v128, v76
	v_fmac_f32_e32 v49, v129, v77
	v_fmac_f32_e32 v49, v130, v78
	v_fmac_f32_e32 v49, v131, v79
	v_min_f32_e32 v132, 0, v49
	v_mul_f32_e64 v49, |v49|, s52
	v_exp_f32_e32 v49, v49
	s_nop 0
	v_add_f32_e32 v49, 1.0, v49
	v_log_f32_e32 v49, v49
	s_nop 0
	v_mul_f32_e32 v133, 0x3f317217, v49
	v_fma_f32 v133, v49, s53, -v133
	v_fmac_f32_e32 v133, 0x3377d1cf, v49
	v_fmac_f32_e32 v133, 0x3f317217, v49
	v_sub_f32_e32 v49, v132, v133
	v_mul_f32_e32 v49, 0x3d800000, v49
	ds_read_b128 v[116:119], v12 offset:2304
	ds_read_b128 v[120:123], v12 offset:2320
	ds_read_b128 v[124:127], v12 offset:2336
	ds_read_b128 v[128:131], v12 offset:2352
	v_mov_b32_e32 v50, v80
	s_waitcnt lgkmcnt(3)
	v_fmac_f32_e32 v50, v116, v64
	v_fmac_f32_e32 v50, v117, v65
	v_fmac_f32_e32 v50, v118, v66
	v_fmac_f32_e32 v50, v119, v67
	s_waitcnt lgkmcnt(2)
	v_fmac_f32_e32 v50, v120, v68
	v_fmac_f32_e32 v50, v121, v69
	v_fmac_f32_e32 v50, v122, v70
	v_fmac_f32_e32 v50, v123, v71
	s_waitcnt lgkmcnt(1)
	v_fmac_f32_e32 v50, v124, v72
	v_fmac_f32_e32 v50, v125, v73
	v_fmac_f32_e32 v50, v126, v74
	v_fmac_f32_e32 v50, v127, v75
	s_waitcnt lgkmcnt(0)
	v_fmac_f32_e32 v50, v128, v76
	v_fmac_f32_e32 v50, v129, v77
	v_fmac_f32_e32 v50, v130, v78
	v_fmac_f32_e32 v50, v131, v79
	v_min_f32_e32 v132, 0, v50
	v_mul_f32_e64 v50, |v50|, s52
	v_exp_f32_e32 v50, v50
	s_nop 0
	v_add_f32_e32 v50, 1.0, v50
	v_log_f32_e32 v50, v50
	s_nop 0
	v_mul_f32_e32 v133, 0x3f317217, v50
	v_fma_f32 v133, v50, s53, -v133
	v_fmac_f32_e32 v133, 0x3377d1cf, v50
	v_fmac_f32_e32 v133, 0x3f317217, v50
	v_sub_f32_e32 v50, v132, v133
	v_mul_f32_e32 v50, 0x3d800000, v50
	ds_read_b128 v[116:119], v12 offset:2432
	ds_read_b128 v[120:123], v12 offset:2448
	ds_read_b128 v[124:127], v12 offset:2464
	ds_read_b128 v[128:131], v12 offset:2480
	v_mov_b32_e32 v51, v80
	s_waitcnt lgkmcnt(3)
	v_fmac_f32_e32 v51, v116, v64
	v_fmac_f32_e32 v51, v117, v65
	v_fmac_f32_e32 v51, v118, v66
	v_fmac_f32_e32 v51, v119, v67
	s_waitcnt lgkmcnt(2)
	v_fmac_f32_e32 v51, v120, v68
	v_fmac_f32_e32 v51, v121, v69
	v_fmac_f32_e32 v51, v122, v70
	v_fmac_f32_e32 v51, v123, v71
	s_waitcnt lgkmcnt(1)
	v_fmac_f32_e32 v51, v124, v72
	v_fmac_f32_e32 v51, v125, v73
	v_fmac_f32_e32 v51, v126, v74
	v_fmac_f32_e32 v51, v127, v75
	s_waitcnt lgkmcnt(0)
	v_fmac_f32_e32 v51, v128, v76
	v_fmac_f32_e32 v51, v129, v77
	v_fmac_f32_e32 v51, v130, v78
	v_fmac_f32_e32 v51, v131, v79
	v_min_f32_e32 v132, 0, v51
	v_mul_f32_e64 v51, |v51|, s52
	v_exp_f32_e32 v51, v51
	s_nop 0
	v_add_f32_e32 v51, 1.0, v51
	v_log_f32_e32 v51, v51
	s_nop 0
	v_mul_f32_e32 v133, 0x3f317217, v51
	v_fma_f32 v133, v51, s53, -v133
	v_fmac_f32_e32 v133, 0x3377d1cf, v51
	v_fmac_f32_e32 v133, 0x3f317217, v51
	v_sub_f32_e32 v51, v132, v133
	v_mul_f32_e32 v51, 0x3d800000, v51
	ds_read_b128 v[116:119], v12 offset:2560
	ds_read_b128 v[120:123], v12 offset:2576
	ds_read_b128 v[124:127], v12 offset:2592
	ds_read_b128 v[128:131], v12 offset:2608
	v_mov_b32_e32 v52, v80
	s_waitcnt lgkmcnt(3)
	v_fmac_f32_e32 v52, v116, v64
	v_fmac_f32_e32 v52, v117, v65
	v_fmac_f32_e32 v52, v118, v66
	v_fmac_f32_e32 v52, v119, v67
	s_waitcnt lgkmcnt(2)
	v_fmac_f32_e32 v52, v120, v68
	v_fmac_f32_e32 v52, v121, v69
	v_fmac_f32_e32 v52, v122, v70
	v_fmac_f32_e32 v52, v123, v71
	s_waitcnt lgkmcnt(1)
	v_fmac_f32_e32 v52, v124, v72
	v_fmac_f32_e32 v52, v125, v73
	v_fmac_f32_e32 v52, v126, v74
	v_fmac_f32_e32 v52, v127, v75
	s_waitcnt lgkmcnt(0)
	v_fmac_f32_e32 v52, v128, v76
	v_fmac_f32_e32 v52, v129, v77
	v_fmac_f32_e32 v52, v130, v78
	v_fmac_f32_e32 v52, v131, v79
	v_min_f32_e32 v132, 0, v52
	v_mul_f32_e64 v52, |v52|, s52
	v_exp_f32_e32 v52, v52
	s_nop 0
	v_add_f32_e32 v52, 1.0, v52
	v_log_f32_e32 v52, v52
	s_nop 0
	v_mul_f32_e32 v133, 0x3f317217, v52
	v_fma_f32 v133, v52, s53, -v133
	v_fmac_f32_e32 v133, 0x3377d1cf, v52
	v_fmac_f32_e32 v133, 0x3f317217, v52
	v_sub_f32_e32 v52, v132, v133
	v_mul_f32_e32 v52, 0x3d800000, v52
	ds_read_b128 v[116:119], v12 offset:2688
	ds_read_b128 v[120:123], v12 offset:2704
	ds_read_b128 v[124:127], v12 offset:2720
	ds_read_b128 v[128:131], v12 offset:2736
	v_mov_b32_e32 v53, v80
	s_waitcnt lgkmcnt(3)
	v_fmac_f32_e32 v53, v116, v64
	v_fmac_f32_e32 v53, v117, v65
	v_fmac_f32_e32 v53, v118, v66
	v_fmac_f32_e32 v53, v119, v67
	s_waitcnt lgkmcnt(2)
	v_fmac_f32_e32 v53, v120, v68
	v_fmac_f32_e32 v53, v121, v69
	v_fmac_f32_e32 v53, v122, v70
	v_fmac_f32_e32 v53, v123, v71
	s_waitcnt lgkmcnt(1)
	v_fmac_f32_e32 v53, v124, v72
	v_fmac_f32_e32 v53, v125, v73
	v_fmac_f32_e32 v53, v126, v74
	v_fmac_f32_e32 v53, v127, v75
	s_waitcnt lgkmcnt(0)
	v_fmac_f32_e32 v53, v128, v76
	v_fmac_f32_e32 v53, v129, v77
	v_fmac_f32_e32 v53, v130, v78
	v_fmac_f32_e32 v53, v131, v79
	v_min_f32_e32 v132, 0, v53
	v_mul_f32_e64 v53, |v53|, s52
	v_exp_f32_e32 v53, v53
	s_nop 0
	v_add_f32_e32 v53, 1.0, v53
	v_log_f32_e32 v53, v53
	s_nop 0
	v_mul_f32_e32 v133, 0x3f317217, v53
	v_fma_f32 v133, v53, s53, -v133
	v_fmac_f32_e32 v133, 0x3377d1cf, v53
	v_fmac_f32_e32 v133, 0x3f317217, v53
	v_sub_f32_e32 v53, v132, v133
	v_mul_f32_e32 v53, 0x3d800000, v53
	ds_read_b128 v[116:119], v12 offset:2816
	ds_read_b128 v[120:123], v12 offset:2832
	ds_read_b128 v[124:127], v12 offset:2848
	ds_read_b128 v[128:131], v12 offset:2864
	v_mov_b32_e32 v54, v80
	s_waitcnt lgkmcnt(3)
; DEVINL float logsig(float z) { return fminf(z, 0.f) - __logf(1.f + __expf(-fabsf(z))); }
; DEVINL void gla_prep_unit(const Params& p, int unit) {
;     ...
;     for (int i = 0; i < 64; ++i) {
;       float z = bias;
; #pragma unroll
;       for (int r = 0; r < 16; ++r) z += afab[i * 32 + dir * 16 + r] * u[r];
;       Gc[i * 128] = logsig(z) * (1.f / 16.f);
	v_fmac_f32_e32 v54, v116, v64
	v_fmac_f32_e32 v54, v117, v65
	v_fmac_f32_e32 v54, v118, v66
	v_fmac_f32_e32 v54, v119, v67
	s_waitcnt lgkmcnt(2)
	v_fmac_f32_e32 v54, v120, v68
	v_fmac_f32_e32 v54, v121, v69
	v_fmac_f32_e32 v54, v122, v70
	v_fmac_f32_e32 v54, v123, v71
	s_waitcnt lgkmcnt(1)
	v_fmac_f32_e32 v54, v124, v72
	v_fmac_f32_e32 v54, v125, v73
	v_fmac_f32_e32 v54, v126, v74
	v_fmac_f32_e32 v54, v127, v75
	s_waitcnt lgkmcnt(0)
	v_fmac_f32_e32 v54, v128, v76
	v_fmac_f32_e32 v54, v129, v77
	v_fmac_f32_e32 v54, v130, v78
	v_fmac_f32_e32 v54, v131, v79
	v_min_f32_e32 v132, 0, v54
	v_mul_f32_e64 v54, |v54|, s52
	v_exp_f32_e32 v54, v54
	s_nop 0
	v_add_f32_e32 v54, 1.0, v54
	v_log_f32_e32 v54, v54
	s_nop 0
	v_mul_f32_e32 v133, 0x3f317217, v54
	v_fma_f32 v133, v54, s53, -v133
	v_fmac_f32_e32 v133, 0x3377d1cf, v54
	v_fmac_f32_e32 v133, 0x3f317217, v54
	v_sub_f32_e32 v54, v132, v133
	v_mul_f32_e32 v54, 0x3d800000, v54
	ds_read_b128 v[116:119], v12 offset:2944
	ds_read_b128 v[120:123], v12 offset:2960
	ds_read_b128 v[124:127], v12 offset:2976
	ds_read_b128 v[128:131], v12 offset:2992
	v_mov_b32_e32 v55, v80
	s_waitcnt lgkmcnt(3)
	v_fmac_f32_e32 v55, v116, v64
	v_fmac_f32_e32 v55, v117, v65
	v_fmac_f32_e32 v55, v118, v66
	v_fmac_f32_e32 v55, v119, v67
	s_waitcnt lgkmcnt(2)
	v_fmac_f32_e32 v55, v120, v68
	v_fmac_f32_e32 v55, v121, v69
	v_fmac_f32_e32 v55, v122, v70
	v_fmac_f32_e32 v55, v123, v71
	s_waitcnt lgkmcnt(1)
	v_fmac_f32_e32 v55, v124, v72
	v_fmac_f32_e32 v55, v125, v73
	v_fmac_f32_e32 v55, v126, v74
	v_fmac_f32_e32 v55, v127, v75
	s_waitcnt lgkmcnt(0)
	v_fmac_f32_e32 v55, v128, v76
	v_fmac_f32_e32 v55, v129, v77
	v_fmac_f32_e32 v55, v130, v78
	v_fmac_f32_e32 v55, v131, v79
	v_min_f32_e32 v132, 0, v55
	v_mul_f32_e64 v55, |v55|, s52
	v_exp_f32_e32 v55, v55
	s_nop 0
	v_add_f32_e32 v55, 1.0, v55
	v_log_f32_e32 v55, v55
	s_nop 0
	v_mul_f32_e32 v133, 0x3f317217, v55
	v_fma_f32 v133, v55, s53, -v133
	v_fmac_f32_e32 v133, 0x3377d1cf, v55
	v_fmac_f32_e32 v133, 0x3f317217, v55
	v_sub_f32_e32 v55, v132, v133
	v_mul_f32_e32 v55, 0x3d800000, v55
	ds_read_b128 v[116:119], v12 offset:3072
	ds_read_b128 v[120:123], v12 offset:3088
	ds_read_b128 v[124:127], v12 offset:3104
	ds_read_b128 v[128:131], v12 offset:3120
	v_mov_b32_e32 v56, v80
	s_waitcnt lgkmcnt(3)
	v_fmac_f32_e32 v56, v116, v64
	v_fmac_f32_e32 v56, v117, v65
	v_fmac_f32_e32 v56, v118, v66
	v_fmac_f32_e32 v56, v119, v67
	s_waitcnt lgkmcnt(2)
	v_fmac_f32_e32 v56, v120, v68
	v_fmac_f32_e32 v56, v121, v69
	v_fmac_f32_e32 v56, v122, v70
	v_fmac_f32_e32 v56, v123, v71
	s_waitcnt lgkmcnt(1)
	v_fmac_f32_e32 v56, v124, v72
	v_fmac_f32_e32 v56, v125, v73
	v_fmac_f32_e32 v56, v126, v74
	v_fmac_f32_e32 v56, v127, v75
	s_waitcnt lgkmcnt(0)
	v_fmac_f32_e32 v56, v128, v76
	v_fmac_f32_e32 v56, v129, v77
	v_fmac_f32_e32 v56, v130, v78
	v_fmac_f32_e32 v56, v131, v79
	v_min_f32_e32 v132, 0, v56
	v_mul_f32_e64 v56, |v56|, s52
	v_exp_f32_e32 v56, v56
	s_nop 0
	v_add_f32_e32 v56, 1.0, v56
	v_log_f32_e32 v56, v56
	s_nop 0
	v_mul_f32_e32 v133, 0x3f317217, v56
	v_fma_f32 v133, v56, s53, -v133
	v_fmac_f32_e32 v133, 0x3377d1cf, v56
	v_fmac_f32_e32 v133, 0x3f317217, v56
	v_sub_f32_e32 v56, v132, v133
	v_mul_f32_e32 v56, 0x3d800000, v56
	ds_read_b128 v[116:119], v12 offset:3200
	ds_read_b128 v[120:123], v12 offset:3216
	ds_read_b128 v[124:127], v12 offset:3232
	ds_read_b128 v[128:131], v12 offset:3248
	v_mov_b32_e32 v57, v80
	s_waitcnt lgkmcnt(3)
	v_fmac_f32_e32 v57, v116, v64
	v_fmac_f32_e32 v57, v117, v65
	v_fmac_f32_e32 v57, v118, v66
	v_fmac_f32_e32 v57, v119, v67
	s_waitcnt lgkmcnt(2)
	v_fmac_f32_e32 v57, v120, v68
	v_fmac_f32_e32 v57, v121, v69
	v_fmac_f32_e32 v57, v122, v70
	v_fmac_f32_e32 v57, v123, v71
	s_waitcnt lgkmcnt(1)
	v_fmac_f32_e32 v57, v124, v72
	v_fmac_f32_e32 v57, v125, v73
	v_fmac_f32_e32 v57, v126, v74
	v_fmac_f32_e32 v57, v127, v75
	s_waitcnt lgkmcnt(0)
	v_fmac_f32_e32 v57, v128, v76
	v_fmac_f32_e32 v57, v129, v77
	v_fmac_f32_e32 v57, v130, v78
	v_fmac_f32_e32 v57, v131, v79
	v_min_f32_e32 v132, 0, v57
	v_mul_f32_e64 v57, |v57|, s52
	v_exp_f32_e32 v57, v57
	s_nop 0
	v_add_f32_e32 v57, 1.0, v57
	v_log_f32_e32 v57, v57
	s_nop 0
	v_mul_f32_e32 v133, 0x3f317217, v57
	v_fma_f32 v133, v57, s53, -v133
	v_fmac_f32_e32 v133, 0x3377d1cf, v57
	v_fmac_f32_e32 v133, 0x3f317217, v57
	v_sub_f32_e32 v57, v132, v133
	v_mul_f32_e32 v57, 0x3d800000, v57
	ds_read_b128 v[116:119], v12 offset:3328
	ds_read_b128 v[120:123], v12 offset:3344
	ds_read_b128 v[124:127], v12 offset:3360
	ds_read_b128 v[128:131], v12 offset:3376
	v_mov_b32_e32 v58, v80
	s_waitcnt lgkmcnt(3)
	v_fmac_f32_e32 v58, v116, v64
	v_fmac_f32_e32 v58, v117, v65
	v_fmac_f32_e32 v58, v118, v66
	v_fmac_f32_e32 v58, v119, v67
	s_waitcnt lgkmcnt(2)
	v_fmac_f32_e32 v58, v120, v68
	v_fmac_f32_e32 v58, v121, v69
	v_fmac_f32_e32 v58, v122, v70
	v_fmac_f32_e32 v58, v123, v71
	s_waitcnt lgkmcnt(1)
	v_fmac_f32_e32 v58, v124, v72
	v_fmac_f32_e32 v58, v125, v73
	v_fmac_f32_e32 v58, v126, v74
	v_fmac_f32_e32 v58, v127, v75
	s_waitcnt lgkmcnt(0)
	v_fmac_f32_e32 v58, v128, v76
	v_fmac_f32_e32 v58, v129, v77
	v_fmac_f32_e32 v58, v130, v78
	v_fmac_f32_e32 v58, v131, v79
	v_min_f32_e32 v132, 0, v58
	v_mul_f32_e64 v58, |v58|, s52
	v_exp_f32_e32 v58, v58
	s_nop 0
	v_add_f32_e32 v58, 1.0, v58
	v_log_f32_e32 v58, v58
	s_nop 0
	v_mul_f32_e32 v133, 0x3f317217, v58
	v_fma_f32 v133, v58, s53, -v133
	v_fmac_f32_e32 v133, 0x3377d1cf, v58
	v_fmac_f32_e32 v133, 0x3f317217, v58
	v_sub_f32_e32 v58, v132, v133
	v_mul_f32_e32 v58, 0x3d800000, v58
	ds_read_b128 v[116:119], v12 offset:3456
	ds_read_b128 v[120:123], v12 offset:3472
	ds_read_b128 v[124:127], v12 offset:3488
	ds_read_b128 v[128:131], v12 offset:3504
	v_mov_b32_e32 v59, v80
	s_waitcnt lgkmcnt(3)
; DEVINL float logsig(float z) { return fminf(z, 0.f) - __logf(1.f + __expf(-fabsf(z))); }
; DEVINL void gla_prep_unit(const Params& p, int unit) {
;     ...
;     for (int i = 0; i < 64; ++i) {
;       float z = bias;
; #pragma unroll
;       for (int r = 0; r < 16; ++r) z += afab[i * 32 + dir * 16 + r] * u[r];
;       Gc[i * 128] = logsig(z) * (1.f / 16.f);
;     }
;     float run = 0.f;
;     if (dir == 0) { for (int i = 0; i < 64; ++i) { run += Gc[i * 128]; Gc[i * 128] = run; } }
;     else { for (int i = 63; i >= 0; --i) { run += Gc[i * 128]; Gc[i * 128] = run; } }
	v_fmac_f32_e32 v59, v116, v64
	v_fmac_f32_e32 v59, v117, v65
	v_fmac_f32_e32 v59, v118, v66
	v_fmac_f32_e32 v59, v119, v67
	s_waitcnt lgkmcnt(2)
	v_fmac_f32_e32 v59, v120, v68
	v_fmac_f32_e32 v59, v121, v69
	v_fmac_f32_e32 v59, v122, v70
	v_fmac_f32_e32 v59, v123, v71
	s_waitcnt lgkmcnt(1)
	v_fmac_f32_e32 v59, v124, v72
	v_fmac_f32_e32 v59, v125, v73
	v_fmac_f32_e32 v59, v126, v74
	v_fmac_f32_e32 v59, v127, v75
	s_waitcnt lgkmcnt(0)
	v_fmac_f32_e32 v59, v128, v76
	v_fmac_f32_e32 v59, v129, v77
	v_fmac_f32_e32 v59, v130, v78
	v_fmac_f32_e32 v59, v131, v79
	v_min_f32_e32 v132, 0, v59
	v_mul_f32_e64 v59, |v59|, s52
	v_exp_f32_e32 v59, v59
	s_nop 0
	v_add_f32_e32 v59, 1.0, v59
	v_log_f32_e32 v59, v59
	s_nop 0
	v_mul_f32_e32 v133, 0x3f317217, v59
	v_fma_f32 v133, v59, s53, -v133
	v_fmac_f32_e32 v133, 0x3377d1cf, v59
	v_fmac_f32_e32 v133, 0x3f317217, v59
	v_sub_f32_e32 v59, v132, v133
	v_mul_f32_e32 v59, 0x3d800000, v59
	ds_read_b128 v[116:119], v12 offset:3584
	ds_read_b128 v[120:123], v12 offset:3600
	ds_read_b128 v[124:127], v12 offset:3616
	ds_read_b128 v[128:131], v12 offset:3632
	v_mov_b32_e32 v60, v80
	s_waitcnt lgkmcnt(3)
	v_fmac_f32_e32 v60, v116, v64
	v_fmac_f32_e32 v60, v117, v65
	v_fmac_f32_e32 v60, v118, v66
	v_fmac_f32_e32 v60, v119, v67
	s_waitcnt lgkmcnt(2)
	v_fmac_f32_e32 v60, v120, v68
	v_fmac_f32_e32 v60, v121, v69
	v_fmac_f32_e32 v60, v122, v70
	v_fmac_f32_e32 v60, v123, v71
	s_waitcnt lgkmcnt(1)
	v_fmac_f32_e32 v60, v124, v72
	v_fmac_f32_e32 v60, v125, v73
	v_fmac_f32_e32 v60, v126, v74
	v_fmac_f32_e32 v60, v127, v75
	s_waitcnt lgkmcnt(0)
	v_fmac_f32_e32 v60, v128, v76
	v_fmac_f32_e32 v60, v129, v77
	v_fmac_f32_e32 v60, v130, v78
	v_fmac_f32_e32 v60, v131, v79
	v_min_f32_e32 v132, 0, v60
	v_mul_f32_e64 v60, |v60|, s52
	v_exp_f32_e32 v60, v60
	s_nop 0
	v_add_f32_e32 v60, 1.0, v60
	v_log_f32_e32 v60, v60
	s_nop 0
	v_mul_f32_e32 v133, 0x3f317217, v60
	v_fma_f32 v133, v60, s53, -v133
	v_fmac_f32_e32 v133, 0x3377d1cf, v60
	v_fmac_f32_e32 v133, 0x3f317217, v60
	v_sub_f32_e32 v60, v132, v133
	v_mul_f32_e32 v60, 0x3d800000, v60
	ds_read_b128 v[116:119], v12 offset:3712
	ds_read_b128 v[120:123], v12 offset:3728
	ds_read_b128 v[124:127], v12 offset:3744
	ds_read_b128 v[128:131], v12 offset:3760
	v_mov_b32_e32 v61, v80
	s_waitcnt lgkmcnt(3)
	v_fmac_f32_e32 v61, v116, v64
	v_fmac_f32_e32 v61, v117, v65
	v_fmac_f32_e32 v61, v118, v66
	v_fmac_f32_e32 v61, v119, v67
	s_waitcnt lgkmcnt(2)
	v_fmac_f32_e32 v61, v120, v68
	v_fmac_f32_e32 v61, v121, v69
	v_fmac_f32_e32 v61, v122, v70
	v_fmac_f32_e32 v61, v123, v71
	s_waitcnt lgkmcnt(1)
	v_fmac_f32_e32 v61, v124, v72
	v_fmac_f32_e32 v61, v125, v73
	v_fmac_f32_e32 v61, v126, v74
	v_fmac_f32_e32 v61, v127, v75
	s_waitcnt lgkmcnt(0)
	v_fmac_f32_e32 v61, v128, v76
	v_fmac_f32_e32 v61, v129, v77
	v_fmac_f32_e32 v61, v130, v78
	v_fmac_f32_e32 v61, v131, v79
	v_min_f32_e32 v132, 0, v61
	v_mul_f32_e64 v61, |v61|, s52
	v_exp_f32_e32 v61, v61
	s_nop 0
	v_add_f32_e32 v61, 1.0, v61
	v_log_f32_e32 v61, v61
	s_nop 0
	v_mul_f32_e32 v133, 0x3f317217, v61
	v_fma_f32 v133, v61, s53, -v133
	v_fmac_f32_e32 v133, 0x3377d1cf, v61
	v_fmac_f32_e32 v133, 0x3f317217, v61
	v_sub_f32_e32 v61, v132, v133
	v_mul_f32_e32 v61, 0x3d800000, v61
	ds_read_b128 v[116:119], v12 offset:3840
	ds_read_b128 v[120:123], v12 offset:3856
	ds_read_b128 v[124:127], v12 offset:3872
	ds_read_b128 v[128:131], v12 offset:3888
	v_mov_b32_e32 v62, v80
	s_waitcnt lgkmcnt(3)
	v_fmac_f32_e32 v62, v116, v64
	v_fmac_f32_e32 v62, v117, v65
	v_fmac_f32_e32 v62, v118, v66
	v_fmac_f32_e32 v62, v119, v67
	s_waitcnt lgkmcnt(2)
	v_fmac_f32_e32 v62, v120, v68
	v_fmac_f32_e32 v62, v121, v69
	v_fmac_f32_e32 v62, v122, v70
	v_fmac_f32_e32 v62, v123, v71
	s_waitcnt lgkmcnt(1)
	v_fmac_f32_e32 v62, v124, v72
	v_fmac_f32_e32 v62, v125, v73
	v_fmac_f32_e32 v62, v126, v74
	v_fmac_f32_e32 v62, v127, v75
	s_waitcnt lgkmcnt(0)
	v_fmac_f32_e32 v62, v128, v76
	v_fmac_f32_e32 v62, v129, v77
	v_fmac_f32_e32 v62, v130, v78
	v_fmac_f32_e32 v62, v131, v79
	v_min_f32_e32 v132, 0, v62
	v_mul_f32_e64 v62, |v62|, s52
	v_exp_f32_e32 v62, v62
	s_nop 0
	v_add_f32_e32 v62, 1.0, v62
	v_log_f32_e32 v62, v62
	s_nop 0
	v_mul_f32_e32 v133, 0x3f317217, v62
	v_fma_f32 v133, v62, s53, -v133
	v_fmac_f32_e32 v133, 0x3377d1cf, v62
	v_fmac_f32_e32 v133, 0x3f317217, v62
	v_sub_f32_e32 v62, v132, v133
	v_mul_f32_e32 v62, 0x3d800000, v62
	ds_read_b128 v[116:119], v12 offset:3968
	ds_read_b128 v[120:123], v12 offset:3984
	ds_read_b128 v[124:127], v12 offset:4000
	ds_read_b128 v[128:131], v12 offset:4016
	v_mov_b32_e32 v63, v80
	s_waitcnt lgkmcnt(3)
	v_fmac_f32_e32 v63, v116, v64
	v_fmac_f32_e32 v63, v117, v65
	v_fmac_f32_e32 v63, v118, v66
	v_fmac_f32_e32 v63, v119, v67
	s_waitcnt lgkmcnt(2)
	v_fmac_f32_e32 v63, v120, v68
	v_fmac_f32_e32 v63, v121, v69
	v_fmac_f32_e32 v63, v122, v70
	v_fmac_f32_e32 v63, v123, v71
	s_waitcnt lgkmcnt(1)
	v_fmac_f32_e32 v63, v124, v72
	v_fmac_f32_e32 v63, v125, v73
	v_fmac_f32_e32 v63, v126, v74
	v_fmac_f32_e32 v63, v127, v75
	s_waitcnt lgkmcnt(0)
	v_fmac_f32_e32 v63, v128, v76
	v_fmac_f32_e32 v63, v129, v77
	v_fmac_f32_e32 v63, v130, v78
	v_fmac_f32_e32 v63, v131, v79
	v_min_f32_e32 v132, 0, v63
	v_mul_f32_e64 v63, |v63|, s52
	v_exp_f32_e32 v63, v63
	s_nop 0
	v_add_f32_e32 v63, 1.0, v63
	v_log_f32_e32 v63, v63
	s_nop 0
	v_mul_f32_e32 v133, 0x3f317217, v63
	v_fma_f32 v133, v63, s53, -v133
	v_fmac_f32_e32 v133, 0x3377d1cf, v63
	v_fmac_f32_e32 v133, 0x3f317217, v63
	v_sub_f32_e32 v63, v132, v133
	v_mul_f32_e32 v63, 0x3d800000, v63
	s_cmp_eq_u32 s71, 0
	s_cbranch_scc0 .Lgl_tot_b
	v_mov_b32_e32 v134, v32
	v_add_f32_e32 v134, v134, v33
	v_add_f32_e32 v134, v134, v34
	v_add_f32_e32 v134, v134, v35
	v_add_f32_e32 v134, v134, v36
	v_add_f32_e32 v134, v134, v37
	v_add_f32_e32 v134, v134, v38
	v_add_f32_e32 v134, v134, v39
	v_add_f32_e32 v134, v134, v40
	v_add_f32_e32 v134, v134, v41
	v_add_f32_e32 v134, v134, v42
	v_add_f32_e32 v134, v134, v43
	v_add_f32_e32 v134, v134, v44
	v_add_f32_e32 v134, v134, v45
	v_add_f32_e32 v134, v134, v46
	v_add_f32_e32 v134, v134, v47
	v_add_f32_e32 v134, v134, v48
	v_add_f32_e32 v134, v134, v49
	v_add_f32_e32 v134, v134, v50
	v_add_f32_e32 v134, v134, v51
	v_add_f32_e32 v134, v134, v52
	v_add_f32_e32 v134, v134, v53
	v_add_f32_e32 v134, v134, v54
	v_add_f32_e32 v134, v134, v55
	v_add_f32_e32 v134, v134, v56
	v_add_f32_e32 v134, v134, v57
	v_add_f32_e32 v134, v134, v58
	v_add_f32_e32 v134, v134, v59
	v_add_f32_e32 v134, v134, v60
	v_add_f32_e32 v134, v134, v61
	v_add_f32_e32 v134, v134, v62
	v_add_f32_e32 v134, v134, v63
	s_branch .Lgl_tot_e
